# stack plus late weight conversions moved out of the bandwidth-bound P6 queue: w_o into P8's tail and w_ple_gate/w_ple_up into P10's tail on workgroups 128..255 (hand-written items, same rounding); que
# baseline (speedup 1.0000x reference)
; __device__ __forceinline__ void relaunder(Frame& F) { int t = threadIdx.x; asm volatile("" : "+v"(t)); F.tid = t; F.lane = t & 63; }
; #define PHASE(k) if (IN(k)) for (int rep_ = (relaunder(F), 0); rep_ < NREP(k); ++rep_)
; #define SEAM(k) do { if (IN(k) && IN((k) + 1)) { if (lo < 0) cooperative_groups::this_grid().sync(); else GRID_BAR(); } } while (0)
; #define SEAM(k) do { } while (0)
; __global__ void __launch_bounds__(NWAVES * 64, 2) fwd_kernel(Args args) {
;     ...
;     PHASE(6) { for (int u = F.vcu; u < 64; u += F.G) mlstm_chain_unit(F, a, u >> 2, u & 3);
;         relaunder(F);
;         unsigned* qctr = (unsigned*)(F.ws + WS_CTL) + CW_QUEUE;
;         for (;;) { relaunder(F);     if (F.tid == 0) F.MISC[16] = atomicAdd(qctr, 1u); __syncthreads(); const int item = (int)F.MISC[16]; __syncthreads(); if (item >= (F.G == 256 ? AUX_TOTAL_256 : AUX_TOTAL)) break; aux_run(F, a, item); } } SEAM(6);
.LBB0_984:
	s_add_u32 s90, s34, 0x30100000
	s_addc_u32 s91, s35, 0
	s_add_u32 s92, s34, 0x3d000000
	s_addc_u32 s93, s35, 0
	s_add_u32 s94, s34, 0x2000
	v_readlane_b32 s3, v245, 41
	s_addc_u32 s95, s35, 0
	s_lshl_b32 s0, s3, 2
	s_add_i32 s41, s20, 0
	s_addk_i32 s0, 0x9800
	v_writelane_b32 v244, s0, 26
	s_cmpk_eq_i32 s96, 0x100
	s_movk_i32 s0, 0x340
	s_cselect_b32 s65, s0, 0x658
	s_cselect_b32 s0, 0x1000, 0
	v_writelane_b32 v244, s0, 27
	s_movk_i32 s0, 0x2100
	s_cselect_b32 s67, s0, 0x6300
	s_add_u32 s0, s34, 0x8c00000
	v_writelane_b32 v244, s0, 28
	s_addc_u32 s0, s35, 0
	v_writelane_b32 v244, s0, 29
	s_add_u32 s0, s34, 0x9400000
	v_writelane_b32 v244, s0, 30
	s_addc_u32 s0, s35, 0
	v_writelane_b32 v244, s0, 31
	s_add_u32 s0, s34, 0x9c00000
	v_writelane_b32 v244, s0, 32
	s_addc_u32 s0, s35, 0
	v_writelane_b32 v244, s0, 33
	s_add_u32 s0, s34, 0x9d00000
	v_writelane_b32 v244, s0, 34
	s_addc_u32 s0, s35, 0
	v_writelane_b32 v244, s0, 35
	s_add_u32 s0, s34, 0xc900000
	v_writelane_b32 v244, s0, 36
	s_addc_u32 s0, s35, 0
	v_writelane_b32 v244, s0, 37
	s_add_u32 s0, s34, 0x7c01000
	v_writelane_b32 v244, s0, 38
	s_addc_u32 s0, s35, 0
	s_add_u32 s97, s34, 0x7c00000
	v_writelane_b32 v244, s0, 39
	s_addc_u32 s82, s35, 0
	s_add_i32 s0, s3, 0xffffe800
	s_add_u32 s70, s34, 0x25300000
	s_addc_u32 s71, s35, 0
	v_writelane_b32 v244, s0, 40
	s_add_u32 s0, s34, 0x27500000
	s_addc_u32 s1, s35, 0
	s_add_u32 s38, s34, 0x34501000
	v_readlane_b32 s4, v245, 35
	v_writelane_b32 v244, s0, 41
	s_addc_u32 s39, s35, 0
	v_readlane_b32 s6, v245, 37
	v_writelane_b32 v244, s1, 42
	v_readlane_b32 s7, v245, 38
	s_add_u32 s0, s6, 0x14f9c840
	s_addc_u32 s1, s7, 0
	v_writelane_b32 v244, s0, 43
	v_readlane_b32 s5, v245, 36
	s_mov_b64 s[78:79], s[6:7]
	v_writelane_b32 v244, s1, 44
	s_add_u32 s0, s34, 0x2fe00000
	s_addc_u32 s1, s35, 0
	s_mov_b64 s[76:77], s[4:5]
	v_writelane_b32 v244, s0, 45
	v_readlane_b32 s4, v245, 50
	v_readlane_b32 s33, v245, 33
	v_writelane_b32 v244, s1, 46
	v_readlane_b32 s8, v245, 54
	v_readlane_b32 s9, v245, 55
	v_readlane_b32 s10, v245, 56
	v_readlane_b32 s11, v245, 57
	v_readlane_b32 s12, v245, 58
	v_readlane_b32 s13, v245, 59
	v_readlane_b32 s14, v245, 60
	v_readlane_b32 s15, v245, 61
	s_bfe_u32 s0, s33, 0x20006
	v_readlane_b32 s16, v245, 62
	v_readlane_b32 s17, v245, 63
	v_readlane_b32 s18, v244, 0
	v_readlane_b32 s19, v244, 1
	s_mov_b64 s[8:9], s[12:13]
	s_lshl_b32 s1, s0, 9
	s_lshl_b32 s0, s0, 16
	s_mov_b64 s[10:11], s[14:15]
	s_mov_b64 s[12:13], s[16:17]
	s_mov_b64 s[14:15], s[18:19]
	v_readlane_b32 s5, v245, 51
	s_add_u32 s4, s14, s0
	s_addc_u32 s5, s15, 0
	v_writelane_b32 v244, s4, 47
	v_readlane_b32 s6, v245, 52
	v_readlane_b32 s7, v245, 53
	v_writelane_b32 v244, s5, 48
	v_mov_b32_e32 v2, v1
	v_readlane_b32 s16, v244, 2
	v_readlane_b32 s17, v244, 3
	s_add_u32 s4, s16, s1
	v_readlane_b32 s18, v244, 4
	v_readlane_b32 s19, v244, 5
	v_readlane_b32 s20, v244, 6
	v_readlane_b32 s21, v244, 7
	v_readlane_b32 s22, v244, 8
	v_readlane_b32 s23, v244, 9
	v_readlane_b32 s24, v244, 10
	v_readlane_b32 s25, v244, 11
	v_readlane_b32 s26, v244, 12
	v_readlane_b32 s27, v244, 13
	v_readlane_b32 s28, v244, 14
	v_readlane_b32 s29, v244, 15
	v_readlane_b32 s30, v244, 16
	v_readlane_b32 s31, v244, 17
	v_writelane_b32 v244, s1, 49
	s_addc_u32 s5, s17, 0
	v_writelane_b32 v244, s4, 50
	s_or_b32 s1, s0, 0x200
	v_mov_b32_e32 v67, 0
	v_writelane_b32 v244, s5, 51
	s_add_u32 s4, s14, s1
	s_addc_u32 s5, s15, 0
	v_writelane_b32 v244, s4, 52
	s_or_b32 s1, s0, 0x400
	v_mbcnt_lo_u32_b32 v2, -1, 0
	v_writelane_b32 v244, s5, 53
	s_add_u32 s4, s14, s1
	s_addc_u32 s5, s15, 0
	s_or_b32 s0, s0, 0x600
	v_writelane_b32 v244, s4, 54
	s_add_u32 s0, s14, s0
	s_addc_u32 s1, s15, 0
	v_writelane_b32 v244, s5, 55
	v_writelane_b32 v244, s0, 56
	v_mov_b32_e32 v121, 0x260
	v_mov_b32_e32 v125, 0x40000
	v_writelane_b32 v244, s1, 57
	s_lshl_b32 s0, s3, 4
	v_writelane_b32 v244, s0, 58
	s_mul_i32 s0, s3, 0xffffc020
	s_add_i32 s0, s41, s0
	v_writelane_b32 v244, s0, 59
	s_add_u32 s0, s34, 0x2fd00000
	v_writelane_b32 v244, s0, 60
	s_addc_u32 s0, s35, 0
	s_cmpk_lt_u32 s33, 0x380
	v_writelane_b32 v244, s0, 61
	s_cselect_b64 s[0:1], -1, 0
	v_writelane_b32 v245, s0, 33
	s_add_u32 s36, s34, 0x27500100
	s_addc_u32 s37, s35, 0
	v_writelane_b32 v245, s1, 34
	s_lshl_b32 s0, s3, 10
	s_add_i32 s0, s0, 0
	s_add_i32 s89, 0, 0x26040
	s_addk_i32 s0, 0x1000
	v_mov_b32_e32 v129, 0x14f9c000
	v_mov_b32_e32 v133, s89
	v_mbcnt_hi_u32_b32 v137, -1, v2
	v_mov_b32_e32 v141, 1
	v_mov_b32_e32 v2, 1.0
	v_mov_b32_e32 v3, v67
	v_mov_b32_e32 v4, v67
	v_mov_b32_e32 v5, v67
	s_movk_i32 s83, 0x4000
	s_mov_b32 s85, 0x8000
	s_mov_b32 s72, 0xc000
	s_mov_b32 s73, 0x10000
	s_mov_b32 s74, 0x14000
	s_mov_b32 s75, 0x18000
	s_mov_b32 s88, 0x1c000
	s_mov_b32 s64, 0x58000
	s_movk_i32 s3, 0x7fff
	s_mov_b32 s66, 0xffff0000
	s_mov_b32 s40, 0x16000
	s_mov_b32 s62, 0xf800000
	s_mov_b32 s33, 0x5040100
	s_add_i32 s84, 0, 0x5000
	s_mov_b32 s87, 0
	s_mov_b64 s[68:69], 0x200
	v_writelane_b32 v244, s0, 62
	s_branch .LBB0_988

; #define GAS __attribute__((address_space(1)))
; #define LAS __attribute__((address_space(3)))
; #define LDS_WAIT() asm volatile("s_waitcnt lgkmcnt(0)" ::: "memory")
; __device__ __forceinline__ unsigned pk2(float lo, float hi) { return f2bf(lo) | (f2bf(hi) << 16); }
;     if (ldt == 0) ldt = K;
;     asm volatile("" : "+v"(lane));
;     const int kb = item / nblk, nb = item % nblk, k0 = 64 * kb, n0 = 32 * nb;
;     { float wv[32];
;       const float* wp = W + (size_t)(k0 + (lane >> 5)) * ldw + n0 + (lane & 31);
; #pragma unroll
;       for (int i = 0; i < 32; ++i) wv[i] = wp[(size_t)(2 * i) * ldw];
; #pragma unroll
;       for (int i = 0; i < 32; ++i) scr[(2 * i + (lane >> 5)) * 33 + (lane & 31)] = wv[i]; }
;     LDS_WAIT(); asm volatile("" ::: "memory");
;     const int c = lane & 7;
;     const int r0 = (mode == 0) ? n0 : (256 * (n0 >> 7) + (n0 & 127) + (mode == 2 ? 128 : 0));
; #pragma unroll
;     for (int j = 0; j < 4; ++j) { const int n = (lane >> 3) + 8 * j; const LAS float* s = scr + (8 * c) * 33 + n;
;         v4u o; o.x = pk2(s[0 * 33], s[1 * 33]); o.y = pk2(s[2 * 33], s[3 * 33]); o.z = pk2(s[4 * 33], s[5 * 33]); o.w = pk2(s[6 * 33], s[7 * 33]);
;         *(GAS v4u*)(WT + (size_t)(r0 + n) * ldt + k0 + 8 * c) = o; }
;     LDS_WAIT(); asm volatile("" ::: "memory");
; }
.LBB0_1254:
	s_cmpk_lg_i32 s96, 0x100
	s_cbranch_scc1 .Lcm8_skip
	s_cmpk_lt_i32 s2, 0x80
	s_cbranch_scc1 .Lcm8_skip
	v_readlane_b32 s36, v244, 6
	v_readlane_b32 s37, v244, 7
	s_add_u32 s38, s34, 0x8c00000
	s_addc_u32 s39, s35, 0
	s_lshl_b32 s44, s2, 3
	s_add_i32 s44, s44, s97
	s_addk_i32 s44, 0xfc00
	s_lshl_b32 s45, s97, 14
	v_mbcnt_lo_u32_b32 v2, -1, 0
	v_mbcnt_hi_u32_b32 v2, -1, v2
	v_lshrrev_b32_e32 v120, 3, v2
	v_and_b32_e32 v121, 7, v2
	v_lshlrev_b32_e32 v3, 13, v120
	v_lshl_add_u32 v3, v121, 4, v3
	v_add_u32_e32 v4, 0x10000, v3
	v_add_u32_e32 v5, 0x20000, v3
	v_add_u32_e32 v6, 0x30000, v3
	v_add_u32_e32 v7, 0x40000, v3
	v_add_u32_e32 v8, 0x50000, v3
	v_add_u32_e32 v9, 0x60000, v3
	v_add_u32_e32 v10, 0x70000, v3
	v_mul_u32_u24_e32 v15, 132, v120
	v_lshl_add_u32 v15, v121, 4, v15
	v_add_u32_e32 v15, s45, v15
	v_add_u32_e32 v16, 1056, v15
	v_add_u32_e32 v17, 2112, v15
	v_add_u32_e32 v18, 3168, v15
	v_add_u32_e32 v19, 4224, v15
	v_add_u32_e32 v20, 5280, v15
	v_add_u32_e32 v21, 6336, v15
	v_add_u32_e32 v22, 7392, v15
	v_mul_u32_u24_e32 v23, 1056, v121
	v_lshl_add_u32 v23, v120, 2, v23
	v_add_u32_e32 v23, s45, v23
	v_mul_u32_u24_e32 v11, 0x1000, v120
	v_lshl_add_u32 v11, v121, 4, v11
	v_add_u32_e32 v12, 0x8000, v11
	v_add_u32_e32 v13, 0x10000, v11
	v_add_u32_e32 v14, 0x18000, v11
	s_add_i32 s48, s44, 0x0
	s_lshr_b32 s46, s48, 6
	s_and_b32 s47, s48, 63
	s_lshl_b32 s40, s46, 19
	s_lshl_b32 s41, s47, 7
	s_add_u32 s40, s40, s41
	s_add_u32 s40, s40, s36
	s_addc_u32 s41, s37, 0
	global_load_dwordx4 v[24:27], v3, s[40:41]
	global_load_dwordx4 v[28:31], v4, s[40:41]
	global_load_dwordx4 v[32:35], v5, s[40:41]
	global_load_dwordx4 v[36:39], v6, s[40:41]
	global_load_dwordx4 v[40:43], v7, s[40:41]
	global_load_dwordx4 v[44:47], v8, s[40:41]
	global_load_dwordx4 v[48:51], v9, s[40:41]
	global_load_dwordx4 v[52:55], v10, s[40:41]
	s_add_i32 s48, s44, 0x400
	s_lshr_b32 s46, s48, 6
	s_and_b32 s47, s48, 63
	s_lshl_b32 s40, s46, 19
	s_lshl_b32 s41, s47, 7
	s_add_u32 s40, s40, s41
	s_add_u32 s40, s40, s36
	s_addc_u32 s41, s37, 0
	global_load_dwordx4 v[56:59], v3, s[40:41]
	global_load_dwordx4 v[60:63], v4, s[40:41]
	global_load_dwordx4 v[64:67], v5, s[40:41]
	global_load_dwordx4 v[68:71], v6, s[40:41]
	global_load_dwordx4 v[72:75], v7, s[40:41]
	global_load_dwordx4 v[76:79], v8, s[40:41]
	global_load_dwordx4 v[80:83], v9, s[40:41]
	global_load_dwordx4 v[84:87], v10, s[40:41]
	s_add_i32 s48, s44, 0x0
	s_lshr_b32 s46, s48, 6
	s_and_b32 s47, s48, 63
	s_mul_i32 s42, s47, 0x20000
	s_lshl_b32 s43, s46, 7
	s_add_u32 s42, s42, s43
	s_add_u32 s42, s42, s38
	s_addc_u32 s43, s39, 0
	s_waitcnt vmcnt(8)
	ds_write2_b32 v15, v24, v25 offset1:1
	ds_write2_b32 v15, v26, v27 offset0:2 offset1:3
	ds_write2_b32 v16, v28, v29 offset1:1
	ds_write2_b32 v16, v30, v31 offset0:2 offset1:3
	ds_write2_b32 v17, v32, v33 offset1:1
	ds_write2_b32 v17, v34, v35 offset0:2 offset1:3
	ds_write2_b32 v18, v36, v37 offset1:1
	ds_write2_b32 v18, v38, v39 offset0:2 offset1:3
	ds_write2_b32 v19, v40, v41 offset1:1
	ds_write2_b32 v19, v42, v43 offset0:2 offset1:3
	ds_write2_b32 v20, v44, v45 offset1:1
	ds_write2_b32 v20, v46, v47 offset0:2 offset1:3
	ds_write2_b32 v21, v48, v49 offset1:1
	ds_write2_b32 v21, v50, v51 offset0:2 offset1:3
	ds_write2_b32 v22, v52, v53 offset1:1
	ds_write2_b32 v22, v54, v55 offset0:2 offset1:3
	s_waitcnt lgkmcnt(0)
	ds_read2_b32 v[120:121], v23 offset0:0 offset1:33
	ds_read2_b32 v[122:123], v23 offset0:66 offset1:99
	ds_read2_b32 v[124:125], v23 offset0:132 offset1:165
	ds_read2_b32 v[126:127], v23 offset0:198 offset1:231
	s_waitcnt lgkmcnt(0)
	v_cvt_pk_bf16_f32 v128, v120, v121
	v_cvt_pk_bf16_f32 v129, v122, v123
	v_cvt_pk_bf16_f32 v130, v124, v125
	v_cvt_pk_bf16_f32 v131, v126, v127
	global_store_dwordx4 v11, v[128:131], s[42:43]
	s_nop 1
	ds_read2_b32 v[120:121], v23 offset0:8 offset1:41
	ds_read2_b32 v[122:123], v23 offset0:74 offset1:107
	ds_read2_b32 v[124:125], v23 offset0:140 offset1:173
	ds_read2_b32 v[126:127], v23 offset0:206 offset1:239
	s_waitcnt lgkmcnt(0)
; #define GAS __attribute__((address_space(1)))
; #define LAS __attribute__((address_space(3)))
; #define LDS_WAIT() asm volatile("s_waitcnt lgkmcnt(0)" ::: "memory")
; __device__ __forceinline__ unsigned pk2(float lo, float hi) { return f2bf(lo) | (f2bf(hi) << 16); }
;     if (ldt == 0) ldt = K;
;     asm volatile("" : "+v"(lane));
;     const int kb = item / nblk, nb = item % nblk, k0 = 64 * kb, n0 = 32 * nb;
;     { float wv[32];
;       const float* wp = W + (size_t)(k0 + (lane >> 5)) * ldw + n0 + (lane & 31);
; #pragma unroll
;       for (int i = 0; i < 32; ++i) wv[i] = wp[(size_t)(2 * i) * ldw];
; #pragma unroll
;       for (int i = 0; i < 32; ++i) scr[(2 * i + (lane >> 5)) * 33 + (lane & 31)] = wv[i]; }
;     LDS_WAIT(); asm volatile("" ::: "memory");
;     const int c = lane & 7;
;     const int r0 = (mode == 0) ? n0 : (256 * (n0 >> 7) + (n0 & 127) + (mode == 2 ? 128 : 0));
; #pragma unroll
;     for (int j = 0; j < 4; ++j) { const int n = (lane >> 3) + 8 * j; const LAS float* s = scr + (8 * c) * 33 + n;
;         v4u o; o.x = pk2(s[0 * 33], s[1 * 33]); o.y = pk2(s[2 * 33], s[3 * 33]); o.z = pk2(s[4 * 33], s[5 * 33]); o.w = pk2(s[6 * 33], s[7 * 33]);
;         *(GAS v4u*)(WT + (size_t)(r0 + n) * ldt + k0 + 8 * c) = o; }
;     LDS_WAIT(); asm volatile("" ::: "memory");
; }
	v_cvt_pk_bf16_f32 v128, v120, v121
	v_cvt_pk_bf16_f32 v129, v122, v123
	v_cvt_pk_bf16_f32 v130, v124, v125
	v_cvt_pk_bf16_f32 v131, v126, v127
	global_store_dwordx4 v12, v[128:131], s[42:43]
	s_nop 1
	ds_read2_b32 v[120:121], v23 offset0:16 offset1:49
	ds_read2_b32 v[122:123], v23 offset0:82 offset1:115
	ds_read2_b32 v[124:125], v23 offset0:148 offset1:181
	ds_read2_b32 v[126:127], v23 offset0:214 offset1:247
	s_waitcnt lgkmcnt(0)
	v_cvt_pk_bf16_f32 v128, v120, v121
	v_cvt_pk_bf16_f32 v129, v122, v123
	v_cvt_pk_bf16_f32 v130, v124, v125
	v_cvt_pk_bf16_f32 v131, v126, v127
	global_store_dwordx4 v13, v[128:131], s[42:43]
	s_nop 1
	ds_read2_b32 v[120:121], v23 offset0:24 offset1:57
	ds_read2_b32 v[122:123], v23 offset0:90 offset1:123
	ds_read2_b32 v[124:125], v23 offset0:156 offset1:189
	ds_read2_b32 v[126:127], v23 offset0:222 offset1:255
	s_waitcnt lgkmcnt(0)
	v_cvt_pk_bf16_f32 v128, v120, v121
	v_cvt_pk_bf16_f32 v129, v122, v123
	v_cvt_pk_bf16_f32 v130, v124, v125
	v_cvt_pk_bf16_f32 v131, v126, v127
	global_store_dwordx4 v14, v[128:131], s[42:43]
	s_nop 1
	s_add_i32 s48, s44, 0x400
	s_lshr_b32 s46, s48, 6
	s_and_b32 s47, s48, 63
	s_mul_i32 s42, s47, 0x20000
	s_lshl_b32 s43, s46, 7
	s_add_u32 s42, s42, s43
	s_add_u32 s42, s42, s38
	s_addc_u32 s43, s39, 0
	s_waitcnt vmcnt(4)
	ds_write2_b32 v15, v56, v57 offset1:1
	ds_write2_b32 v15, v58, v59 offset0:2 offset1:3
	ds_write2_b32 v16, v60, v61 offset1:1
	ds_write2_b32 v16, v62, v63 offset0:2 offset1:3
	ds_write2_b32 v17, v64, v65 offset1:1
	ds_write2_b32 v17, v66, v67 offset0:2 offset1:3
	ds_write2_b32 v18, v68, v69 offset1:1
	ds_write2_b32 v18, v70, v71 offset0:2 offset1:3
	ds_write2_b32 v19, v72, v73 offset1:1
	ds_write2_b32 v19, v74, v75 offset0:2 offset1:3
	ds_write2_b32 v20, v76, v77 offset1:1
	ds_write2_b32 v20, v78, v79 offset0:2 offset1:3
	ds_write2_b32 v21, v80, v81 offset1:1
	ds_write2_b32 v21, v82, v83 offset0:2 offset1:3
	ds_write2_b32 v22, v84, v85 offset1:1
	ds_write2_b32 v22, v86, v87 offset0:2 offset1:3
	s_waitcnt lgkmcnt(0)
	ds_read2_b32 v[120:121], v23 offset0:0 offset1:33
	ds_read2_b32 v[122:123], v23 offset0:66 offset1:99
	ds_read2_b32 v[124:125], v23 offset0:132 offset1:165
	ds_read2_b32 v[126:127], v23 offset0:198 offset1:231
	s_waitcnt lgkmcnt(0)
	v_cvt_pk_bf16_f32 v128, v120, v121
	v_cvt_pk_bf16_f32 v129, v122, v123
	v_cvt_pk_bf16_f32 v130, v124, v125
	v_cvt_pk_bf16_f32 v131, v126, v127
	global_store_dwordx4 v11, v[128:131], s[42:43]
	s_nop 1
	ds_read2_b32 v[120:121], v23 offset0:8 offset1:41
	ds_read2_b32 v[122:123], v23 offset0:74 offset1:107
	ds_read2_b32 v[124:125], v23 offset0:140 offset1:173
	ds_read2_b32 v[126:127], v23 offset0:206 offset1:239
	s_waitcnt lgkmcnt(0)
	v_cvt_pk_bf16_f32 v128, v120, v121
	v_cvt_pk_bf16_f32 v129, v122, v123
	v_cvt_pk_bf16_f32 v130, v124, v125
	v_cvt_pk_bf16_f32 v131, v126, v127
	global_store_dwordx4 v12, v[128:131], s[42:43]
	s_nop 1
	ds_read2_b32 v[120:121], v23 offset0:16 offset1:49
	ds_read2_b32 v[122:123], v23 offset0:82 offset1:115
	ds_read2_b32 v[124:125], v23 offset0:148 offset1:181
	ds_read2_b32 v[126:127], v23 offset0:214 offset1:247
	s_waitcnt lgkmcnt(0)
	v_cvt_pk_bf16_f32 v128, v120, v121
	v_cvt_pk_bf16_f32 v129, v122, v123
	v_cvt_pk_bf16_f32 v130, v124, v125
	v_cvt_pk_bf16_f32 v131, v126, v127
	global_store_dwordx4 v13, v[128:131], s[42:43]
	s_nop 1
	ds_read2_b32 v[120:121], v23 offset0:24 offset1:57
	ds_read2_b32 v[122:123], v23 offset0:90 offset1:123
	ds_read2_b32 v[124:125], v23 offset0:156 offset1:189
	ds_read2_b32 v[126:127], v23 offset0:222 offset1:255
	s_waitcnt lgkmcnt(0)
	v_cvt_pk_bf16_f32 v128, v120, v121
	v_cvt_pk_bf16_f32 v129, v122, v123
	v_cvt_pk_bf16_f32 v130, v124, v125
	v_cvt_pk_bf16_f32 v131, v126, v127
	global_store_dwordx4 v14, v[128:131], s[42:43]
	s_nop 1

; #define GAS __attribute__((address_space(1)))
; #define LAS __attribute__((address_space(3)))
; #define LDS_WAIT() asm volatile("s_waitcnt lgkmcnt(0)" ::: "memory")
; __device__ __forceinline__ unsigned pk2(float lo, float hi) { return f2bf(lo) | (f2bf(hi) << 16); }
;     if (ldt == 0) ldt = K;
;     asm volatile("" : "+v"(lane));
;     const int kb = item / nblk, nb = item % nblk, k0 = 64 * kb, n0 = 32 * nb;
;     { float wv[32];
;       const float* wp = W + (size_t)(k0 + (lane >> 5)) * ldw + n0 + (lane & 31);
; #pragma unroll
;       for (int i = 0; i < 32; ++i) wv[i] = wp[(size_t)(2 * i) * ldw];
; #pragma unroll
;       for (int i = 0; i < 32; ++i) scr[(2 * i + (lane >> 5)) * 33 + (lane & 31)] = wv[i]; }
;     LDS_WAIT(); asm volatile("" ::: "memory");
;     const int c = lane & 7;
;     const int r0 = (mode == 0) ? n0 : (256 * (n0 >> 7) + (n0 & 127) + (mode == 2 ? 128 : 0));
; #pragma unroll
;     for (int j = 0; j < 4; ++j) { const int n = (lane >> 3) + 8 * j; const LAS float* s = scr + (8 * c) * 33 + n;
;         v4u o; o.x = pk2(s[0 * 33], s[1 * 33]); o.y = pk2(s[2 * 33], s[3 * 33]); o.z = pk2(s[4 * 33], s[5 * 33]); o.w = pk2(s[6 * 33], s[7 * 33]);
;         *(GAS v4u*)(WT + (size_t)(r0 + n) * ldt + k0 + 8 * c) = o; }
;     LDS_WAIT(); asm volatile("" ::: "memory");
; }
.LBB0_1435:
	s_cmpk_lg_i32 s96, 0x100
	s_cbranch_scc1 .Lcm10_skip
	s_cmpk_lt_i32 s2, 0x80
	s_cbranch_scc1 .Lcm10_skip
	v_readlane_b32 s36, v245, 4
	v_readlane_b32 s37, v245, 5
	s_add_u32 s38, s34, 0x9400000
	s_addc_u32 s39, s35, 0
	v_readlane_b32 s50, v245, 6
	v_readlane_b32 s51, v245, 7
	s_add_u32 s52, s34, 0x9c00000
	s_addc_u32 s53, s35, 0
	s_lshl_b32 s44, s2, 3
	s_add_i32 s44, s44, s97
	s_addk_i32 s44, 0xfc00
	s_lshl_b32 s45, s97, 14
	v_mbcnt_lo_u32_b32 v2, -1, 0
	v_mbcnt_hi_u32_b32 v2, -1, v2
	v_lshrrev_b32_e32 v120, 3, v2
	v_and_b32_e32 v121, 7, v2
	v_lshlrev_b32_e32 v3, 13, v120
	v_lshl_add_u32 v3, v121, 4, v3
	v_add_u32_e32 v4, 0x10000, v3
	v_add_u32_e32 v5, 0x20000, v3
	v_add_u32_e32 v6, 0x30000, v3
	v_add_u32_e32 v7, 0x40000, v3
	v_add_u32_e32 v8, 0x50000, v3
	v_add_u32_e32 v9, 0x60000, v3
	v_add_u32_e32 v10, 0x70000, v3
	v_mul_u32_u24_e32 v15, 132, v120
	v_lshl_add_u32 v15, v121, 4, v15
	v_add_u32_e32 v15, s45, v15
	v_add_u32_e32 v16, 1056, v15
	v_add_u32_e32 v17, 2112, v15
	v_add_u32_e32 v18, 3168, v15
	v_add_u32_e32 v19, 4224, v15
	v_add_u32_e32 v20, 5280, v15
	v_add_u32_e32 v21, 6336, v15
	v_add_u32_e32 v22, 7392, v15
	v_mul_u32_u24_e32 v23, 1056, v121
	v_lshl_add_u32 v23, v120, 2, v23
	v_add_u32_e32 v23, s45, v23
	v_mul_u32_u24_e32 v11, 0x1000, v120
	v_lshl_add_u32 v11, v121, 4, v11
	v_add_u32_e32 v12, 0x8000, v11
	v_add_u32_e32 v13, 0x10000, v11
	v_add_u32_e32 v14, 0x18000, v11
	v_mul_u32_u24_e32 v132, 0x200, v120
	v_lshl_add_u32 v132, v121, 4, v132
	v_add_u32_e32 v133, 0x1000, v132
	v_add_u32_e32 v134, 0x2000, v132
	v_add_u32_e32 v135, 0x3000, v132
	s_add_i32 s48, s44, 0x0
	s_lshr_b32 s46, s48, 6
	s_and_b32 s47, s48, 63
	s_lshl_b32 s40, s46, 19
	s_lshl_b32 s41, s47, 7
	s_add_u32 s40, s40, s41
	s_add_u32 s40, s40, s36
	s_addc_u32 s41, s37, 0
	global_load_dwordx4 v[24:27], v3, s[40:41]
	global_load_dwordx4 v[28:31], v4, s[40:41]
	global_load_dwordx4 v[32:35], v5, s[40:41]
	global_load_dwordx4 v[36:39], v6, s[40:41]
	global_load_dwordx4 v[40:43], v7, s[40:41]
	global_load_dwordx4 v[44:47], v8, s[40:41]
	global_load_dwordx4 v[48:51], v9, s[40:41]
	global_load_dwordx4 v[52:55], v10, s[40:41]
	s_add_i32 s48, s44, 0x400
	s_lshr_b32 s46, s48, 6
	s_and_b32 s47, s48, 63
	s_lshl_b32 s40, s46, 19
	s_lshl_b32 s41, s47, 7
	s_add_u32 s40, s40, s41
	s_add_u32 s40, s40, s36
	s_addc_u32 s41, s37, 0
	global_load_dwordx4 v[56:59], v3, s[40:41]
	global_load_dwordx4 v[60:63], v4, s[40:41]
	global_load_dwordx4 v[64:67], v5, s[40:41]
	global_load_dwordx4 v[68:71], v6, s[40:41]
	global_load_dwordx4 v[72:75], v7, s[40:41]
	global_load_dwordx4 v[76:79], v8, s[40:41]
	global_load_dwordx4 v[80:83], v9, s[40:41]
	global_load_dwordx4 v[84:87], v10, s[40:41]
	s_cmpk_lt_i32 s44, 0x100
	s_cbranch_scc0 .Lcm10_nol2
	s_add_i32 s48, s44, 0x0
	s_lshr_b32 s46, s48, 6
	s_and_b32 s47, s48, 63
	s_lshl_b32 s40, s46, 19
	s_lshl_b32 s41, s47, 7
	s_add_u32 s40, s40, s41
	s_add_u32 s40, s40, s50
	s_addc_u32 s41, s51, 0
	global_load_dwordx4 v[88:91], v3, s[40:41]
	global_load_dwordx4 v[92:95], v4, s[40:41]
	global_load_dwordx4 v[96:99], v5, s[40:41]
	global_load_dwordx4 v[100:103], v6, s[40:41]
	global_load_dwordx4 v[104:107], v7, s[40:41]
	global_load_dwordx4 v[108:111], v8, s[40:41]
	global_load_dwordx4 v[112:115], v9, s[40:41]
	global_load_dwordx4 v[116:119], v10, s[40:41]
.Lcm10_nol2:
	s_add_i32 s48, s44, 0x0
	s_lshr_b32 s46, s48, 6
	s_and_b32 s47, s48, 63
	s_mul_i32 s42, s47, 0x20000
	s_lshl_b32 s43, s46, 7
	s_add_u32 s42, s42, s43
	s_add_u32 s42, s42, s38
	s_addc_u32 s43, s39, 0
	s_waitcnt vmcnt(8)
	ds_write2_b32 v15, v24, v25 offset1:1
	ds_write2_b32 v15, v26, v27 offset0:2 offset1:3
	ds_write2_b32 v16, v28, v29 offset1:1
	ds_write2_b32 v16, v30, v31 offset0:2 offset1:3
	ds_write2_b32 v17, v32, v33 offset1:1
	ds_write2_b32 v17, v34, v35 offset0:2 offset1:3
	ds_write2_b32 v18, v36, v37 offset1:1
	ds_write2_b32 v18, v38, v39 offset0:2 offset1:3
	ds_write2_b32 v19, v40, v41 offset1:1
	ds_write2_b32 v19, v42, v43 offset0:2 offset1:3
	ds_write2_b32 v20, v44, v45 offset1:1
	ds_write2_b32 v20, v46, v47 offset0:2 offset1:3
	ds_write2_b32 v21, v48, v49 offset1:1
	ds_write2_b32 v21, v50, v51 offset0:2 offset1:3
	ds_write2_b32 v22, v52, v53 offset1:1
	ds_write2_b32 v22, v54, v55 offset0:2 offset1:3
	s_waitcnt lgkmcnt(0)
	ds_read2_b32 v[120:121], v23 offset0:0 offset1:33
	ds_read2_b32 v[122:123], v23 offset0:66 offset1:99
	ds_read2_b32 v[124:125], v23 offset0:132 offset1:165
	ds_read2_b32 v[126:127], v23 offset0:198 offset1:231
	s_waitcnt lgkmcnt(0)
	v_cvt_pk_bf16_f32 v128, v120, v121
	v_cvt_pk_bf16_f32 v129, v122, v123
	v_cvt_pk_bf16_f32 v130, v124, v125
	v_cvt_pk_bf16_f32 v131, v126, v127
	global_store_dwordx4 v11, v[128:131], s[42:43]
	s_nop 1
	ds_read2_b32 v[120:121], v23 offset0:8 offset1:41
	ds_read2_b32 v[122:123], v23 offset0:74 offset1:107
	ds_read2_b32 v[124:125], v23 offset0:140 offset1:173
	ds_read2_b32 v[126:127], v23 offset0:206 offset1:239
	s_waitcnt lgkmcnt(0)
	v_cvt_pk_bf16_f32 v128, v120, v121
	v_cvt_pk_bf16_f32 v129, v122, v123
	v_cvt_pk_bf16_f32 v130, v124, v125
	v_cvt_pk_bf16_f32 v131, v126, v127
	global_store_dwordx4 v12, v[128:131], s[42:43]
	s_nop 1
	ds_read2_b32 v[120:121], v23 offset0:16 offset1:49
	ds_read2_b32 v[122:123], v23 offset0:82 offset1:115
	ds_read2_b32 v[124:125], v23 offset0:148 offset1:181
	ds_read2_b32 v[126:127], v23 offset0:214 offset1:247
	s_waitcnt lgkmcnt(0)
	v_cvt_pk_bf16_f32 v128, v120, v121
	v_cvt_pk_bf16_f32 v129, v122, v123
	v_cvt_pk_bf16_f32 v130, v124, v125
	v_cvt_pk_bf16_f32 v131, v126, v127
	global_store_dwordx4 v13, v[128:131], s[42:43]
	s_nop 1
	ds_read2_b32 v[120:121], v23 offset0:24 offset1:57
	ds_read2_b32 v[122:123], v23 offset0:90 offset1:123
	ds_read2_b32 v[124:125], v23 offset0:156 offset1:189
	ds_read2_b32 v[126:127], v23 offset0:222 offset1:255
	s_waitcnt lgkmcnt(0)
; #define GAS __attribute__((address_space(1)))
; #define LAS __attribute__((address_space(3)))
; #define LDS_WAIT() asm volatile("s_waitcnt lgkmcnt(0)" ::: "memory")
; __device__ __forceinline__ unsigned pk2(float lo, float hi) { return f2bf(lo) | (f2bf(hi) << 16); }
;     if (ldt == 0) ldt = K;
;     asm volatile("" : "+v"(lane));
;     const int kb = item / nblk, nb = item % nblk, k0 = 64 * kb, n0 = 32 * nb;
;     { float wv[32];
;       const float* wp = W + (size_t)(k0 + (lane >> 5)) * ldw + n0 + (lane & 31);
; #pragma unroll
;       for (int i = 0; i < 32; ++i) wv[i] = wp[(size_t)(2 * i) * ldw];
; #pragma unroll
;       for (int i = 0; i < 32; ++i) scr[(2 * i + (lane >> 5)) * 33 + (lane & 31)] = wv[i]; }
;     LDS_WAIT(); asm volatile("" ::: "memory");
;     const int c = lane & 7;
;     const int r0 = (mode == 0) ? n0 : (256 * (n0 >> 7) + (n0 & 127) + (mode == 2 ? 128 : 0));
; #pragma unroll
;     for (int j = 0; j < 4; ++j) { const int n = (lane >> 3) + 8 * j; const LAS float* s = scr + (8 * c) * 33 + n;
;         v4u o; o.x = pk2(s[0 * 33], s[1 * 33]); o.y = pk2(s[2 * 33], s[3 * 33]); o.z = pk2(s[4 * 33], s[5 * 33]); o.w = pk2(s[6 * 33], s[7 * 33]);
;         *(GAS v4u*)(WT + (size_t)(r0 + n) * ldt + k0 + 8 * c) = o; }
;     LDS_WAIT(); asm volatile("" ::: "memory");
; }
	v_cvt_pk_bf16_f32 v128, v120, v121
	v_cvt_pk_bf16_f32 v129, v122, v123
	v_cvt_pk_bf16_f32 v130, v124, v125
	v_cvt_pk_bf16_f32 v131, v126, v127
	global_store_dwordx4 v14, v[128:131], s[42:43]
	s_nop 1
	s_add_i32 s48, s44, 0x400
	s_lshr_b32 s46, s48, 6
	s_and_b32 s47, s48, 63
	s_mul_i32 s42, s47, 0x20000
	s_lshl_b32 s43, s46, 7
	s_add_u32 s42, s42, s43
	s_add_u32 s42, s42, s38
	s_addc_u32 s43, s39, 0
	s_waitcnt vmcnt(4)
	ds_write2_b32 v15, v56, v57 offset1:1
	ds_write2_b32 v15, v58, v59 offset0:2 offset1:3
	ds_write2_b32 v16, v60, v61 offset1:1
	ds_write2_b32 v16, v62, v63 offset0:2 offset1:3
	ds_write2_b32 v17, v64, v65 offset1:1
	ds_write2_b32 v17, v66, v67 offset0:2 offset1:3
	ds_write2_b32 v18, v68, v69 offset1:1
	ds_write2_b32 v18, v70, v71 offset0:2 offset1:3
	ds_write2_b32 v19, v72, v73 offset1:1
	ds_write2_b32 v19, v74, v75 offset0:2 offset1:3
	ds_write2_b32 v20, v76, v77 offset1:1
	ds_write2_b32 v20, v78, v79 offset0:2 offset1:3
	ds_write2_b32 v21, v80, v81 offset1:1
	ds_write2_b32 v21, v82, v83 offset0:2 offset1:3
	ds_write2_b32 v22, v84, v85 offset1:1
	ds_write2_b32 v22, v86, v87 offset0:2 offset1:3
	s_waitcnt lgkmcnt(0)
	ds_read2_b32 v[120:121], v23 offset0:0 offset1:33
	ds_read2_b32 v[122:123], v23 offset0:66 offset1:99
	ds_read2_b32 v[124:125], v23 offset0:132 offset1:165
	ds_read2_b32 v[126:127], v23 offset0:198 offset1:231
	s_waitcnt lgkmcnt(0)
	v_cvt_pk_bf16_f32 v128, v120, v121
	v_cvt_pk_bf16_f32 v129, v122, v123
	v_cvt_pk_bf16_f32 v130, v124, v125
	v_cvt_pk_bf16_f32 v131, v126, v127
	global_store_dwordx4 v11, v[128:131], s[42:43]
	s_nop 1
	ds_read2_b32 v[120:121], v23 offset0:8 offset1:41
	ds_read2_b32 v[122:123], v23 offset0:74 offset1:107
	ds_read2_b32 v[124:125], v23 offset0:140 offset1:173
	ds_read2_b32 v[126:127], v23 offset0:206 offset1:239
	s_waitcnt lgkmcnt(0)
	v_cvt_pk_bf16_f32 v128, v120, v121
	v_cvt_pk_bf16_f32 v129, v122, v123
	v_cvt_pk_bf16_f32 v130, v124, v125
	v_cvt_pk_bf16_f32 v131, v126, v127
	global_store_dwordx4 v12, v[128:131], s[42:43]
	s_nop 1
	ds_read2_b32 v[120:121], v23 offset0:16 offset1:49
	ds_read2_b32 v[122:123], v23 offset0:82 offset1:115
	ds_read2_b32 v[124:125], v23 offset0:148 offset1:181
	ds_read2_b32 v[126:127], v23 offset0:214 offset1:247
	s_waitcnt lgkmcnt(0)
	v_cvt_pk_bf16_f32 v128, v120, v121
	v_cvt_pk_bf16_f32 v129, v122, v123
	v_cvt_pk_bf16_f32 v130, v124, v125
	v_cvt_pk_bf16_f32 v131, v126, v127
	global_store_dwordx4 v13, v[128:131], s[42:43]
	s_nop 1
	ds_read2_b32 v[120:121], v23 offset0:24 offset1:57
	ds_read2_b32 v[122:123], v23 offset0:90 offset1:123
	ds_read2_b32 v[124:125], v23 offset0:156 offset1:189
	ds_read2_b32 v[126:127], v23 offset0:222 offset1:255
	s_waitcnt lgkmcnt(0)
	v_cvt_pk_bf16_f32 v128, v120, v121
	v_cvt_pk_bf16_f32 v129, v122, v123
	v_cvt_pk_bf16_f32 v130, v124, v125
	v_cvt_pk_bf16_f32 v131, v126, v127
	global_store_dwordx4 v14, v[128:131], s[42:43]
	s_nop 1
	s_cmpk_lt_i32 s44, 0x100
	s_cbranch_scc0 .Lcm10_skip
	s_add_i32 s48, s44, 0x0
	s_lshr_b32 s46, s48, 6
	s_and_b32 s47, s48, 63
	s_mul_i32 s42, s47, 0x4000
	s_lshl_b32 s43, s46, 7
	s_add_u32 s42, s42, s43
	s_add_u32 s42, s42, s52
	s_addc_u32 s43, s53, 0
	s_waitcnt vmcnt(8)
	ds_write2_b32 v15, v88, v89 offset1:1
	ds_write2_b32 v15, v90, v91 offset0:2 offset1:3
	ds_write2_b32 v16, v92, v93 offset1:1
	ds_write2_b32 v16, v94, v95 offset0:2 offset1:3
	ds_write2_b32 v17, v96, v97 offset1:1
	ds_write2_b32 v17, v98, v99 offset0:2 offset1:3
	ds_write2_b32 v18, v100, v101 offset1:1
	ds_write2_b32 v18, v102, v103 offset0:2 offset1:3
	ds_write2_b32 v19, v104, v105 offset1:1
	ds_write2_b32 v19, v106, v107 offset0:2 offset1:3
	ds_write2_b32 v20, v108, v109 offset1:1
	ds_write2_b32 v20, v110, v111 offset0:2 offset1:3
	ds_write2_b32 v21, v112, v113 offset1:1
	ds_write2_b32 v21, v114, v115 offset0:2 offset1:3
	ds_write2_b32 v22, v116, v117 offset1:1
	ds_write2_b32 v22, v118, v119 offset0:2 offset1:3
	s_waitcnt lgkmcnt(0)
	ds_read2_b32 v[120:121], v23 offset0:0 offset1:33
	ds_read2_b32 v[122:123], v23 offset0:66 offset1:99
	ds_read2_b32 v[124:125], v23 offset0:132 offset1:165
	ds_read2_b32 v[126:127], v23 offset0:198 offset1:231
	s_waitcnt lgkmcnt(0)
	v_cvt_pk_bf16_f32 v128, v120, v121
	v_cvt_pk_bf16_f32 v129, v122, v123
	v_cvt_pk_bf16_f32 v130, v124, v125
	v_cvt_pk_bf16_f32 v131, v126, v127
	global_store_dwordx4 v132, v[128:131], s[42:43]
	s_nop 1
	ds_read2_b32 v[120:121], v23 offset0:8 offset1:41
	ds_read2_b32 v[122:123], v23 offset0:74 offset1:107
	ds_read2_b32 v[124:125], v23 offset0:140 offset1:173
	ds_read2_b32 v[126:127], v23 offset0:206 offset1:239
	s_waitcnt lgkmcnt(0)
	v_cvt_pk_bf16_f32 v128, v120, v121
	v_cvt_pk_bf16_f32 v129, v122, v123
	v_cvt_pk_bf16_f32 v130, v124, v125
	v_cvt_pk_bf16_f32 v131, v126, v127
	global_store_dwordx4 v133, v[128:131], s[42:43]
	s_nop 1
	ds_read2_b32 v[120:121], v23 offset0:16 offset1:49
	ds_read2_b32 v[122:123], v23 offset0:82 offset1:115
	ds_read2_b32 v[124:125], v23 offset0:148 offset1:181
	ds_read2_b32 v[126:127], v23 offset0:214 offset1:247
	s_waitcnt lgkmcnt(0)
	v_cvt_pk_bf16_f32 v128, v120, v121
	v_cvt_pk_bf16_f32 v129, v122, v123
	v_cvt_pk_bf16_f32 v130, v124, v125
	v_cvt_pk_bf16_f32 v131, v126, v127
	global_store_dwordx4 v134, v[128:131], s[42:43]
	s_nop 1
	ds_read2_b32 v[120:121], v23 offset0:24 offset1:57
	ds_read2_b32 v[122:123], v23 offset0:90 offset1:123
	ds_read2_b32 v[124:125], v23 offset0:156 offset1:189
	ds_read2_b32 v[126:127], v23 offset0:222 offset1:255
	s_waitcnt lgkmcnt(0)
	v_cvt_pk_bf16_f32 v128, v120, v121
	v_cvt_pk_bf16_f32 v129, v122, v123
	v_cvt_pk_bf16_f32 v130, v124, v125
	v_cvt_pk_bf16_f32 v131, v126, v127
	global_store_dwordx4 v135, v[128:131], s[42:43]
	s_nop 1
